# baseline (speedup 1.0000x reference)
.LBB0_749:
.LBB0_750:
	ds_read_b128 v[124:127], v227 offset:36864
	ds_read_b128 v[202:205], v227 offset:41472
	ds_read_b128 v[230:233], v227 offset:46080
	ds_read_b128 v[234:237], v227 offset:50688
	s_min_u32 s2, s1, 0xfb
	s_min_u32 s3, s1, 0xfd
	v_exp_f32_e32 v229, v128
	v_exp_f32_e32 v252, v144
	v_exp_f32_e32 v14, v129
	v_exp_f32_e32 v0, v145
	s_waitcnt lgkmcnt(3)
	v_mfma_f32_32x32x16_bf16 v[64:79], v[124:127], v[120:123], v[64:79]
	v_add_f32_e32 v15, v229, v252
	v_exp_f32_e32 v213, v130
	v_pk_add_f32 v[128:129], v[14:15], v[0:1]
	v_exp_f32_e32 v214, v146
	v_exp_f32_e32 v206, v131
	ds_read_b128 v[124:127], v227 offset:36896
	ds_read_b128 v[238:241], v227 offset:41504
	ds_read_b128 v[242:245], v227 offset:46112
	ds_read_b128 v[246:249], v227 offset:50720
	s_waitcnt lgkmcnt(6)
	v_mfma_f32_32x32x16_bf16 v[48:63], v[202:205], v[120:123], v[48:63]
	v_add_f32_e64 v202, v128, v128
	v_add_f32_e64 v203, v128, v129
	v_exp_f32_e32 v202, v147
	v_add_f32_e32 v207, v213, v214
	s_lshl_b32 s2, s2, 17
	v_max_i32_e32 v15, v14, v0
	s_add_i32 s42, s2, 0x80000
	s_lshl_b32 s2, s3, 14
	s_waitcnt lgkmcnt(5)
	v_mfma_f32_32x32x16_bf16 v[32:47], v[230:233], v[120:123], v[32:47]
	v_max3_i32 v15, v229, v252, v15
	v_max_i32_e32 v128, v213, v214
	v_lshl_add_u64 v[250:251], v[192:193], 0, s[42:43]
	v_lshl_add_u64 v[180:181], v[196:197], 0, s[42:43]
	s_add_i32 s42, s2, 0x8000
	v_lshl_add_u64 v[182:183], v[194:195], 0, s[42:43]
	v_lshl_add_u64 v[184:185], v[198:199], 0, s[42:43]
	s_waitcnt lgkmcnt(4)
	v_mfma_f32_32x32x16_bf16 v[16:31], v[234:237], v[120:123], v[16:31]
	v_add_f32_e64 v120, v206, v202
	v_add_f32_e64 v121, v207, v203
	v_add_f32_e64 v204, v120, v120
	v_add_f32_e64 v205, v120, v121
	v_max_i32_e32 v120, v206, v202
	v_max3_i32 v15, v15, v128, v120
	ds_read_b128 v[120:123], v227 offset:36928
	ds_read_b128 v[230:233], v227 offset:41536
	ds_read_b128 v[234:237], v227 offset:46144
	ds_read_b128 v[176:179], v227 offset:50752
	s_waitcnt vmcnt(3)
	ds_write_b128 v221, v[10:13] offset:18432
	s_waitcnt vmcnt(2)
	ds_write_b128 v221, v[112:115] offset:23040
	s_waitcnt vmcnt(1)
	ds_write_b128 v222, v[168:171] offset:55296
	s_waitcnt vmcnt(0)
	ds_write_b128 v222, v[172:175] offset:64512
	global_load_dwordx4 v[128:131], v[250:251], off
	global_load_dwordx4 v[144:147], v[180:181], off
	global_load_dwordx4 v[168:171], v[182:183], off
	global_load_dwordx4 v[172:175], v[184:185], off
	v_exp_f32_e32 v203, v132
	v_exp_f32_e32 v207, v148
	v_exp_f32_e32 v180, v133
	v_exp_f32_e32 v204, v149
	s_waitcnt lgkmcnt(11)
	v_mfma_f32_32x32x16_bf16 v[64:79], v[124:127], v[116:119], v[64:79]
	v_add_f32_e32 v181, v203, v207
	v_max_i32_e32 v12, v203, v207
	v_add_f32_e64 v10, v180, v204
	v_add_f32_e64 v11, v181, v205
	v_exp_f32_e32 v181, v134
	v_exp_f32_e32 v205, v150
	v_pk_add_f32 v[182:183], v[10:11], v[10:11] op_sel_hi:[0,1]
	v_max_i32_e32 v10, v180, v204
	s_waitcnt lgkmcnt(10)
	v_mfma_f32_32x32x16_bf16 v[48:63], v[238:241], v[116:119], v[48:63]
	v_max3_i32 v15, v15, v12, v10
	v_max_i32_e32 v126, v181, v205
	v_add_f32_e32 v185, v181, v205
	s_waitcnt lgkmcnt(9)
	v_mfma_f32_32x32x16_bf16 v[32:47], v[242:245], v[116:119], v[32:47]
	s_waitcnt lgkmcnt(8)
	v_mfma_f32_32x32x16_bf16 v[16:31], v[246:249], v[116:119], v[16:31]
	v_exp_f32_e32 v184, v135
	v_exp_f32_e32 v182, v151
	s_waitcnt lgkmcnt(7)
	v_mfma_f32_32x32x16_bf16 v[64:79], v[120:123], v[6:9], v[64:79]
	ds_read_b128 v[10:13], v227 offset:36960
	ds_read_b128 v[112:115], v227 offset:41568
	ds_read_b128 v[116:119], v227 offset:46176
	ds_read_b128 v[120:123], v227 offset:50784
	v_add_f32_e64 v124, v184, v182
	v_add_f32_e64 v125, v185, v183
	v_exp_f32_e32 v183, v136
	v_exp_f32_e32 v185, v152
	s_waitcnt lgkmcnt(10)
	v_mfma_f32_32x32x16_bf16 v[48:63], v[230:233], v[6:9], v[48:63]
	v_add_f32_e64 v230, v124, v124
	v_add_f32_e64 v231, v124, v125
	v_exp_f32_e32 v232, v137
	v_exp_f32_e32 v230, v153
	v_max_i32_e32 v124, v184, v182
	v_add_f32_e32 v233, v183, v185
	v_max3_i32 v15, v15, v126, v124
	v_pk_add_f32 v[124:125], v[232:233], v[230:231]
	s_waitcnt lgkmcnt(9)
	v_mfma_f32_32x32x16_bf16 v[32:47], v[234:237], v[6:9], v[32:47]
	v_max_i32_e32 v126, v183, v185
	v_add_f32_e64 v234, v124, v124
	v_add_f32_e64 v235, v124, v125
	v_max_i32_e32 v124, v232, v230
	v_max3_i32 v15, v15, v126, v124
	s_waitcnt lgkmcnt(8)
	v_mfma_f32_32x32x16_bf16 v[16:31], v[176:179], v[6:9], v[16:31]
	v_exp_f32_e32 v231, v138
	v_exp_f32_e32 v233, v154
	s_waitcnt lgkmcnt(3)
	v_mfma_f32_32x32x16_bf16 v[64:79], v[10:13], v[2:5], v[64:79]
	v_exp_f32_e32 v236, v139
	v_exp_f32_e32 v234, v155
	ds_read_b128 v[6:9], v223
	ds_read_b128 v[10:13], v223 offset:32
	ds_read_b128 v[132:135], v223 offset:4608
	ds_read_b128 v[148:151], v223 offset:4640
	v_add_f32_e32 v237, v231, v233
	v_exp_f32_e32 v156, v156
	s_waitcnt lgkmcnt(6)
	v_mfma_f32_32x32x16_bf16 v[48:63], v[112:115], v[2:5], v[48:63]
	v_add_f32_e64 v112, v236, v234
	v_add_f32_e64 v113, v237, v235
	v_exp_f32_e32 v235, v140
	v_max_i32_e32 v114, v231, v233
	v_pk_add_f32 v[238:239], v[112:113], v[112:113] op_sel_hi:[0,1]
	v_max_i32_e32 v112, v236, v234
	v_max3_i32 v15, v15, v114, v112
	v_add_f32_e32 v241, v235, v156
	s_waitcnt lgkmcnt(5)
	v_mfma_f32_32x32x16_bf16 v[32:47], v[116:119], v[2:5], v[32:47]
	v_max_i32_e32 v237, v235, v156
	s_waitcnt lgkmcnt(4)
	v_mfma_f32_32x32x16_bf16 v[16:31], v[120:123], v[2:5], v[16:31]
	s_waitcnt lgkmcnt(3)
	v_mfma_f32_32x32x16_bf16 v[112:127], v[6:9], v[160:163], v[96:111]
	v_exp_f32_e32 v240, v141
	v_exp_f32_e32 v238, v157
	v_exp_f32_e32 v158, v158
	ds_read_b128 v[2:5], v223 offset:64
	ds_read_b128 v[136:139], v223 offset:96
	ds_read_b128 v[6:9], v223 offset:4672
	ds_read_b128 v[152:155], v223 offset:4704
	v_pk_add_f32 v[140:141], v[240:241], v[238:239]
	s_nop 0
	v_pk_add_f32 v[140:141], v[140:141], v[140:141] op_sel_hi:[0,1]
	s_waitcnt lgkmcnt(5)
	v_mfma_f32_32x32x16_bf16 v[80:95], v[132:135], v[160:163], v[96:111]
	v_exp_f32_e32 v239, v142
	v_exp_f32_e32 v142, v143
	v_exp_f32_e32 v140, v159
	ds_read_b128 v[132:135], v224
	ds_read_b128 v[176:179], v224 offset:1024
	v_add_f32_e32 v143, v239, v158
	v_max_i32_e32 v157, v240, v238
	v_mfma_f32_32x32x16_bf16 v[112:127], v[10:13], v[164:167], v[112:127]
	v_add_f32_e64 v10, v142, v140
	v_add_f32_e64 v11, v143, v141
	v_max3_i32 v12, v15, v237, v157
	v_max_i32_e32 v13, v239, v158
	v_add_f32_e32 v141, v10, v11
	v_max_i32_e32 v10, v142, v140
	v_max3_i32 v15, v12, v13, v10
	s_waitcnt lgkmcnt(6)
	v_mfma_f32_32x32x16_bf16 v[80:95], v[148:151], v[164:167], v[80:95]
	s_waitcnt lgkmcnt(1)
	v_mfma_f32_32x32x16_bf16 v[112:127], v[2:5], v[132:135], v[112:127]
	v_cvt_pk_bf16_f32 v10, v229, v14
	v_cvt_pk_bf16_f32 v11, v213, v206
	v_cvt_pk_bf16_f32 v12, v203, v180
	v_cvt_pk_bf16_f32 v13, v181, v184
	v_cvt_pk_bf16_f32 v2, v252, v0
	v_cvt_pk_bf16_f32 v3, v214, v202
	v_cvt_pk_bf16_f32 v4, v207, v204
	v_mfma_f32_32x32x16_bf16 v[80:95], v[6:9], v[132:135], v[80:95]
	v_cvt_pk_bf16_f32 v6, v183, v232
	v_cvt_pk_bf16_f32 v7, v231, v236
	v_cvt_pk_bf16_f32 v8, v235, v240
	v_cvt_pk_bf16_f32 v9, v239, v142
	v_cvt_pk_bf16_f32 v5, v205, v182
	v_cvt_pk_bf16_f32 v132, v185, v230
	v_cvt_pk_bf16_f32 v133, v233, v234
	s_waitcnt lgkmcnt(0)
	v_mfma_f32_32x32x16_bf16 v[112:127], v[136:139], v[176:179], v[112:127]
	v_cvt_pk_bf16_f32 v134, v156, v238
	v_cvt_pk_bf16_f32 v135, v158, v140
	v_mfma_f32_32x32x16_bf16 v[80:95], v[152:155], v[176:179], v[80:95]
	v_add_f32_e32 v204, v228, v141
	v_cmp_lt_i32_e32 vcc, s64, v15
	s_barrier
	s_cbranch_vccz .LBB0_746
	v_max_i32_e32 v0, 0, v15
	ds_bpermute_b32 v14, v189, v0
	v_and_b32_e32 v15, 0xffff0000, v10
	s_waitcnt lgkmcnt(0)
	v_max_i32_e32 v0, v0, v14
	v_log_f32_e32 v0, v0
	v_lshlrev_b32_e32 v14, 16, v10
	v_max_f32_e32 v97, 0, v0
	v_exp_f32_e64 v0, -v97
	v_add_f32_e32 v226, v226, v97
	v_xor_b32_e32 v96, 0x80000000, v226
	v_sub_f32_e32 v95, v95, v97
	v_pk_mul_f32 v[14:15], v[0:1], v[14:15] op_sel_hi:[0,1]
	v_cvt_pk_bf16_f32 v10, v14, v15
	v_lshlrev_b32_e32 v14, 16, v11
	v_and_b32_e32 v15, 0xffff0000, v11
	v_pk_mul_f32 v[14:15], v[0:1], v[14:15] op_sel_hi:[0,1]
	v_cvt_pk_bf16_f32 v11, v14, v15
	v_lshlrev_b32_e32 v14, 16, v12
	v_and_b32_e32 v15, 0xffff0000, v12
	v_pk_mul_f32 v[14:15], v[0:1], v[14:15] op_sel_hi:[0,1]
	v_cvt_pk_bf16_f32 v12, v14, v15
	v_lshlrev_b32_e32 v14, 16, v13
	v_and_b32_e32 v15, 0xffff0000, v13
	v_pk_mul_f32 v[14:15], v[0:1], v[14:15] op_sel_hi:[0,1]
	v_cvt_pk_bf16_f32 v13, v14, v15
	v_lshlrev_b32_e32 v14, 16, v6
	v_and_b32_e32 v15, 0xffff0000, v6
	v_pk_mul_f32 v[14:15], v[0:1], v[14:15] op_sel_hi:[0,1]
	v_cvt_pk_bf16_f32 v6, v14, v15
	v_lshlrev_b32_e32 v14, 16, v7
	v_and_b32_e32 v15, 0xffff0000, v7
	v_pk_mul_f32 v[14:15], v[0:1], v[14:15] op_sel_hi:[0,1]
	v_cvt_pk_bf16_f32 v7, v14, v15
	v_lshlrev_b32_e32 v14, 16, v8
	v_and_b32_e32 v15, 0xffff0000, v8
	v_pk_mul_f32 v[14:15], v[0:1], v[14:15] op_sel_hi:[0,1]
	v_cvt_pk_bf16_f32 v8, v14, v15
	v_lshlrev_b32_e32 v14, 16, v9
	v_and_b32_e32 v15, 0xffff0000, v9
	v_pk_mul_f32 v[14:15], v[0:1], v[14:15] op_sel_hi:[0,1]
	v_cvt_pk_bf16_f32 v9, v14, v15
	v_lshlrev_b32_e32 v14, 16, v2
	v_and_b32_e32 v15, 0xffff0000, v2
	v_pk_mul_f32 v[14:15], v[0:1], v[14:15] op_sel_hi:[0,1]
	v_cvt_pk_bf16_f32 v2, v14, v15
	v_lshlrev_b32_e32 v14, 16, v3
	v_and_b32_e32 v15, 0xffff0000, v3
	v_pk_mul_f32 v[14:15], v[0:1], v[14:15] op_sel_hi:[0,1]
	v_cvt_pk_bf16_f32 v3, v14, v15
	v_lshlrev_b32_e32 v14, 16, v4
	v_and_b32_e32 v15, 0xffff0000, v4
	v_pk_mul_f32 v[14:15], v[0:1], v[14:15] op_sel_hi:[0,1]
	v_cvt_pk_bf16_f32 v4, v14, v15
	v_lshlrev_b32_e32 v14, 16, v5
	v_and_b32_e32 v15, 0xffff0000, v5
	v_pk_mul_f32 v[14:15], v[0:1], v[14:15] op_sel_hi:[0,1]
	v_cvt_pk_bf16_f32 v5, v14, v15
	v_lshlrev_b32_e32 v14, 16, v132
	v_and_b32_e32 v15, 0xffff0000, v132
	v_pk_mul_f32 v[14:15], v[0:1], v[14:15] op_sel_hi:[0,1]
	v_cvt_pk_bf16_f32 v132, v14, v15
	v_lshlrev_b32_e32 v14, 16, v133
	v_and_b32_e32 v15, 0xffff0000, v133
	v_pk_mul_f32 v[14:15], v[0:1], v[14:15] op_sel_hi:[0,1]
	v_cvt_pk_bf16_f32 v133, v14, v15
	v_lshlrev_b32_e32 v14, 16, v134
	v_and_b32_e32 v15, 0xffff0000, v134
	v_pk_mul_f32 v[14:15], v[0:1], v[14:15] op_sel_hi:[0,1]
	v_cvt_pk_bf16_f32 v134, v14, v15
	v_lshlrev_b32_e32 v14, 16, v135
	v_and_b32_e32 v15, 0xffff0000, v135
	v_pk_mul_f32 v[14:15], v[0:1], v[14:15] op_sel_hi:[0,1]
	v_pk_mul_f32 v[78:79], v[78:79], v[0:1] op_sel_hi:[1,0]
	v_pk_mul_f32 v[76:77], v[76:77], v[0:1] op_sel_hi:[1,0]
	v_pk_mul_f32 v[74:75], v[74:75], v[0:1] op_sel_hi:[1,0]
	v_pk_mul_f32 v[72:73], v[72:73], v[0:1] op_sel_hi:[1,0]
	v_pk_mul_f32 v[70:71], v[70:71], v[0:1] op_sel_hi:[1,0]
	v_pk_mul_f32 v[68:69], v[68:69], v[0:1] op_sel_hi:[1,0]
	v_pk_mul_f32 v[66:67], v[66:67], v[0:1] op_sel_hi:[1,0]
	v_pk_mul_f32 v[64:65], v[64:65], v[0:1] op_sel_hi:[1,0]
	v_pk_mul_f32 v[62:63], v[62:63], v[0:1] op_sel_hi:[1,0]
	v_pk_mul_f32 v[60:61], v[60:61], v[0:1] op_sel_hi:[1,0]
	v_pk_mul_f32 v[58:59], v[58:59], v[0:1] op_sel_hi:[1,0]
	v_pk_mul_f32 v[56:57], v[56:57], v[0:1] op_sel_hi:[1,0]
	v_pk_mul_f32 v[54:55], v[54:55], v[0:1] op_sel_hi:[1,0]
	v_pk_mul_f32 v[52:53], v[52:53], v[0:1] op_sel_hi:[1,0]
	v_pk_mul_f32 v[50:51], v[50:51], v[0:1] op_sel_hi:[1,0]
	v_pk_mul_f32 v[48:49], v[48:49], v[0:1] op_sel_hi:[1,0]
	v_pk_mul_f32 v[46:47], v[46:47], v[0:1] op_sel_hi:[1,0]
	v_pk_mul_f32 v[44:45], v[44:45], v[0:1] op_sel_hi:[1,0]
	v_pk_mul_f32 v[42:43], v[42:43], v[0:1] op_sel_hi:[1,0]
	v_pk_mul_f32 v[40:41], v[40:41], v[0:1] op_sel_hi:[1,0]
	v_pk_mul_f32 v[38:39], v[38:39], v[0:1] op_sel_hi:[1,0]
	v_pk_mul_f32 v[36:37], v[36:37], v[0:1] op_sel_hi:[1,0]
	v_pk_mul_f32 v[34:35], v[34:35], v[0:1] op_sel_hi:[1,0]
	v_pk_mul_f32 v[32:33], v[32:33], v[0:1] op_sel_hi:[1,0]
	v_pk_mul_f32 v[30:31], v[30:31], v[0:1] op_sel_hi:[1,0]
	v_pk_mul_f32 v[28:29], v[28:29], v[0:1] op_sel_hi:[1,0]
	v_pk_mul_f32 v[26:27], v[26:27], v[0:1] op_sel_hi:[1,0]
	v_pk_mul_f32 v[24:25], v[24:25], v[0:1] op_sel_hi:[1,0]
	v_pk_mul_f32 v[22:23], v[22:23], v[0:1] op_sel_hi:[1,0]
	v_pk_mul_f32 v[20:21], v[20:21], v[0:1] op_sel_hi:[1,0]
	v_pk_mul_f32 v[18:19], v[18:19], v[0:1] op_sel_hi:[1,0]
	v_pk_mul_f32 v[16:17], v[16:17], v[0:1] op_sel_hi:[1,0]
	v_sub_f32_e32 v94, v94, v97
	v_sub_f32_e32 v93, v93, v97
	v_sub_f32_e32 v92, v92, v97
	v_sub_f32_e32 v91, v91, v97
	v_sub_f32_e32 v90, v90, v97
	v_sub_f32_e32 v89, v89, v97
	v_sub_f32_e32 v88, v88, v97
	v_sub_f32_e32 v87, v87, v97
	v_sub_f32_e32 v86, v86, v97
	v_sub_f32_e32 v85, v85, v97
	v_sub_f32_e32 v84, v84, v97
	v_sub_f32_e32 v83, v83, v97
	v_sub_f32_e32 v82, v82, v97
	v_sub_f32_e32 v81, v81, v97
	v_sub_f32_e32 v80, v80, v97
	v_cvt_pk_bf16_f32 v135, v14, v15
	v_sub_f32_e32 v127, v127, v97
	v_sub_f32_e32 v126, v126, v97
	v_sub_f32_e32 v125, v125, v97
	v_sub_f32_e32 v124, v124, v97
	v_sub_f32_e32 v123, v123, v97
	v_sub_f32_e32 v122, v122, v97
	v_sub_f32_e32 v121, v121, v97
	v_sub_f32_e32 v120, v120, v97
	v_sub_f32_e32 v119, v119, v97
	v_sub_f32_e32 v118, v118, v97
	v_sub_f32_e32 v117, v117, v97
	v_sub_f32_e32 v116, v116, v97
	v_sub_f32_e32 v115, v115, v97
	v_sub_f32_e32 v114, v114, v97
	v_sub_f32_e32 v113, v113, v97
	v_sub_f32_e32 v112, v112, v97
	v_mul_f32_e32 v204, v204, v0
	v_mov_b32_e32 v97, v96
	v_mov_b32_e32 v98, v96
	v_mov_b32_e32 v99, v96
	v_mov_b32_e32 v100, v96
	v_mov_b32_e32 v101, v96
	v_mov_b32_e32 v102, v96
	v_mov_b32_e32 v103, v96
	v_mov_b32_e32 v104, v96
	v_mov_b32_e32 v105, v96
	v_mov_b32_e32 v106, v96
	v_mov_b32_e32 v107, v96
	v_mov_b32_e32 v108, v96
	v_mov_b32_e32 v109, v96
	v_mov_b32_e32 v110, v96
	v_mov_b32_e32 v111, v96
	s_branch .LBB0_746
